# run the deferred weight transposes + p->bf16 right after each workgroup's first P2 queue item (earlier is better: leaves the dynamic queue time to rebalance)
# speedup vs baseline: 1.0062x; 1.0007x over previous
.LBB0_259:
	s_add_i32 s98, s98, 1
	s_cmp_eq_u32 s98, 1
	s_cbranch_scc0 .Lp0b_no
	s_movk_i32 s98, 0x1000
	s_or_b32 s99, s99, 4
	s_branch .Lp0b_call
